# g11 + P1 redundant epilogue-entry barrier removed
# speedup vs baseline: 1.0062x; 1.0043x over previous
; DI unsigned cvtpk(float lo, float hi) { const f32x2_ v = {lo, hi}; return __builtin_bit_cast(unsigned, __builtin_convertvector(v, bf16x2_)); }
; DI void store4(u16* dst, f32x4 v) { uint2 w; w.x = cvtpk(v[0], v[1]); w.y = cvtpk(v[2], v[3]); *(uint2*)dst = w; }
; DI void phase1(const Params& p, const Sched& sched, unsigned char* smem) {
;     ...
;       constexpr int EST = 136;
;       u16* Ls = (u16*)smem;
;       __syncthreads();
; #pragma unroll
;       for (int mi = 0; mi < 4; ++mi)
; #pragma unroll
;         for (int ni = 0; ni < 8; ++ni) store4(Ls + (wt * 128 + ni * 16 + lr) * EST + wf * 64 + mi * 16 + lq * 4, acc[mi][ni]);
;       __syncthreads();
.LBB0_267:
	s_or_b64 exec, exec, s[26:27]
	v_mul_u32_u24_e32 v129, 0x88, v160
	v_lshlrev_b32_e32 v128, 1, v159
	v_lshlrev_b32_e32 v129, 1, v129
	v_add3_u32 v128, v128, v158, v129
	v_cvt_pk_bf16_f32 v28, v28, v29
	v_cvt_pk_bf16_f32 v29, v30, v31
	v_cvt_pk_bf16_f32 v0, v0, v1
	v_cvt_pk_bf16_f32 v1, v2, v3
	v_cvt_pk_bf16_f32 v72, v72, v73
	v_cvt_pk_bf16_f32 v73, v74, v75
	v_add_u32_e32 v74, 0x1000, v128
	v_cvt_pk_bf16_f32 v30, v32, v33
	v_cvt_pk_bf16_f32 v31, v34, v35
	ds_write2_b64 v128, v[28:29], v[0:1] offset0:8 offset1:12
	v_cvt_pk_bf16_f32 v0, v4, v5
	v_cvt_pk_bf16_f32 v1, v6, v7
	v_cvt_pk_bf16_f32 v116, v116, v117
	v_cvt_pk_bf16_f32 v117, v118, v119
	v_cvt_pk_bf16_f32 v64, v64, v65
	v_cvt_pk_bf16_f32 v65, v66, v67
	v_add_u32_e32 v66, 0x2000, v128
	v_cvt_pk_bf16_f32 v32, v40, v41
	v_cvt_pk_bf16_f32 v33, v42, v43
	ds_write2_b64 v74, v[30:31], v[0:1] offset0:40 offset1:44
	v_cvt_pk_bf16_f32 v0, v8, v9
	v_cvt_pk_bf16_f32 v1, v10, v11
	v_cvt_pk_bf16_f32 v112, v112, v113
	v_cvt_pk_bf16_f32 v113, v114, v115
	ds_write2_b64 v66, v[116:117], v[64:65] offset0:64 offset1:68
	v_cvt_pk_bf16_f32 v64, v68, v69
	v_cvt_pk_bf16_f32 v65, v70, v71
	v_add_u32_e32 v67, 0x3000, v128
	v_cvt_pk_bf16_f32 v34, v44, v45
	v_cvt_pk_bf16_f32 v35, v46, v47
	ds_write2_b64 v66, v[32:33], v[0:1] offset0:72 offset1:76
	v_cvt_pk_bf16_f32 v0, v12, v13
	v_cvt_pk_bf16_f32 v1, v14, v15
	v_cvt_pk_bf16_f32 v108, v108, v109
	v_cvt_pk_bf16_f32 v109, v110, v111
	ds_write2_b64 v67, v[112:113], v[64:65] offset0:96 offset1:100
	v_cvt_pk_bf16_f32 v64, v76, v77
	v_cvt_pk_bf16_f32 v65, v78, v79
	v_add_u32_e32 v68, 0x4000, v128
	v_cvt_pk_bf16_f32 v40, v48, v49
	v_cvt_pk_bf16_f32 v41, v50, v51
	ds_write2_b64 v67, v[34:35], v[0:1] offset0:104 offset1:108
	v_cvt_pk_bf16_f32 v0, v16, v17
	v_cvt_pk_bf16_f32 v1, v18, v19
	v_cvt_pk_bf16_f32 v104, v104, v105
	v_cvt_pk_bf16_f32 v105, v106, v107
	ds_write2_b64 v68, v[108:109], v[64:65] offset0:128 offset1:132
	v_cvt_pk_bf16_f32 v64, v84, v85
	v_cvt_pk_bf16_f32 v65, v86, v87
	v_add_u32_e32 v69, 0x5000, v128
	v_cvt_pk_bf16_f32 v42, v52, v53
	v_cvt_pk_bf16_f32 v43, v54, v55
	ds_write2_b64 v68, v[40:41], v[0:1] offset0:136 offset1:140
	v_cvt_pk_bf16_f32 v0, v20, v21
	v_cvt_pk_bf16_f32 v1, v22, v23
	v_cvt_pk_bf16_f32 v100, v100, v101
	v_cvt_pk_bf16_f32 v101, v102, v103
	ds_write2_b64 v69, v[104:105], v[64:65] offset0:160 offset1:164
	v_cvt_pk_bf16_f32 v64, v88, v89
	v_cvt_pk_bf16_f32 v65, v90, v91
	v_add_u32_e32 v70, 0x6000, v128
	v_cvt_pk_bf16_f32 v44, v56, v57
	v_cvt_pk_bf16_f32 v45, v58, v59
	ds_write2_b64 v69, v[42:43], v[0:1] offset0:168 offset1:172
	v_cvt_pk_bf16_f32 v0, v24, v25
	v_cvt_pk_bf16_f32 v1, v26, v27
	v_cvt_pk_bf16_f32 v124, v124, v125
	v_cvt_pk_bf16_f32 v125, v126, v127
	v_cvt_pk_bf16_f32 v120, v120, v121
	v_cvt_pk_bf16_f32 v121, v122, v123
	v_cvt_pk_bf16_f32 v96, v96, v97
	v_cvt_pk_bf16_f32 v97, v98, v99
	v_cvt_pk_bf16_f32 v80, v80, v81
	v_cvt_pk_bf16_f32 v81, v82, v83
	ds_write2_b64 v70, v[100:101], v[64:65] offset0:192 offset1:196
	v_cvt_pk_bf16_f32 v64, v92, v93
	v_cvt_pk_bf16_f32 v65, v94, v95
	v_add_u32_e32 v71, 0x7000, v128
	v_cvt_pk_bf16_f32 v46, v60, v61
	v_cvt_pk_bf16_f32 v47, v62, v63
	ds_write2_b64 v70, v[44:45], v[0:1] offset0:200 offset1:204
	v_cvt_pk_bf16_f32 v0, v36, v37
	v_cvt_pk_bf16_f32 v1, v38, v39
	v_mov_b32_e32 v10, v218
	ds_write2_b64 v128, v[124:125], v[80:81] offset1:4
	ds_write2_b64 v74, v[120:121], v[72:73] offset0:32 offset1:36
	ds_write2_b64 v71, v[96:97], v[64:65] offset0:224 offset1:228
	ds_write2_b64 v71, v[46:47], v[0:1] offset0:232 offset1:236
	s_waitcnt lgkmcnt(0)
	s_barrier
; DI int tidx() { int t = __builtin_amdgcn_workitem_id_x(); asm volatile("" : "+v"(t)); return t; }
; template <class F> DI void for_tiles_st(int ntm, int ntn, const Sched& sc, F f) {
;     ...
;       for (int qq = sc.rank; qq < 64; qq += sc.nloc) f(sm * 8 + (qq >> 3), sn * 8 + (qq & 7));
; DI void phase1(const Params& p, const Sched& sched, unsigned char* smem) {
;     ...
;       const int tid = tidx();
; #pragma unroll
;       for (int i = 0; i < 16; ++i) {
;         const int c = tid + 256 * i, row = c >> 4, ch = (c & 15) * 8;
;         *(u32x4*)(dst + (size_t)(t0 + row) * ld + (f0 - cb) + ch) = *(const u32x4*)(Ls + row * EST + ch);
;       }
	s_lshl_b32 s25, s61, 7
	v_lshlrev_b32_e32 v0, 4, v10
	v_and_b32_e32 v152, 0xf0, v0
	v_ashrrev_i32_e32 v4, 4, v10
	v_mad_u64_u32 v[0:1], s[26:27], v4, s51, v[152:153]
	v_add_u32_e32 v4, s60, v4
	v_mad_i64_i32 v[4:5], s[26:27], s24, v4, 0
	s_add_i32 s26, s62, s25
	s_ashr_i32 s27, s26, 31
	ds_read_b128 v[0:3], v0
	v_lshl_add_u64 v[4:5], v[4:5], 1, s[22:23]
	s_lshl_b64 s[26:27], s[26:27], 1
	v_lshl_add_u64 v[4:5], v[4:5], 0, s[26:27]
	v_lshl_add_u64 v[8:9], v[4:5], 0, v[152:153]
	v_add_u32_e32 v4, 0x100, v10
	v_ashrrev_i32_e32 v11, 4, v4
	v_mad_u64_u32 v[4:5], s[28:29], v11, s51, v[152:153]
	ds_read_b128 v[4:7], v4
	s_waitcnt lgkmcnt(1)
	global_store_dwordx4 v[8:9], v[0:3], off
	s_add_i32 s58, s58, s31
	s_nop 0
	v_add_u32_e32 v0, s60, v11
	v_mad_i64_i32 v[0:1], s[28:29], s24, v0, 0
	v_lshl_add_u64 v[0:1], v[0:1], 1, s[22:23]
	v_lshl_add_u64 v[0:1], v[0:1], 0, s[26:27]
	v_lshl_add_u64 v[0:1], v[0:1], 0, v[152:153]
	s_waitcnt lgkmcnt(0)
	global_store_dwordx4 v[0:1], v[4:7], off
	v_add_u32_e32 v0, 0x200, v10
	s_nop 0
	v_ashrrev_i32_e32 v4, 4, v0
	v_mad_u64_u32 v[0:1], s[28:29], v4, s51, v[152:153]
	v_add_u32_e32 v4, s60, v4
	v_mad_i64_i32 v[4:5], s[28:29], s24, v4, 0
	ds_read_b128 v[0:3], v0
	v_lshl_add_u64 v[4:5], v[4:5], 1, s[22:23]
	v_lshl_add_u64 v[4:5], v[4:5], 0, s[26:27]
	v_lshl_add_u64 v[8:9], v[4:5], 0, v[152:153]
	v_add_u32_e32 v4, 0x300, v10
	v_ashrrev_i32_e32 v11, 4, v4
	v_mad_u64_u32 v[4:5], s[28:29], v11, s51, v[152:153]
	ds_read_b128 v[4:7], v4
	s_waitcnt lgkmcnt(1)
	global_store_dwordx4 v[8:9], v[0:3], off
	s_nop 1
	v_add_u32_e32 v0, s60, v11
	v_mad_i64_i32 v[0:1], s[28:29], s24, v0, 0
	v_lshl_add_u64 v[0:1], v[0:1], 1, s[22:23]
	v_lshl_add_u64 v[0:1], v[0:1], 0, s[26:27]
	v_lshl_add_u64 v[0:1], v[0:1], 0, v[152:153]
	s_waitcnt lgkmcnt(0)
	global_store_dwordx4 v[0:1], v[4:7], off
	v_add_u32_e32 v0, 0x400, v10
	s_nop 0
	v_ashrrev_i32_e32 v4, 4, v0
	v_mad_u64_u32 v[0:1], s[28:29], v4, s51, v[152:153]
	v_add_u32_e32 v4, s60, v4
	v_mad_i64_i32 v[4:5], s[28:29], s24, v4, 0
	ds_read_b128 v[0:3], v0
	v_lshl_add_u64 v[4:5], v[4:5], 1, s[22:23]
	v_lshl_add_u64 v[4:5], v[4:5], 0, s[26:27]
	v_lshl_add_u64 v[8:9], v[4:5], 0, v[152:153]
	v_add_u32_e32 v4, 0x500, v10
	v_ashrrev_i32_e32 v11, 4, v4
	v_mad_u64_u32 v[4:5], s[28:29], v11, s51, v[152:153]
	ds_read_b128 v[4:7], v4
	s_waitcnt lgkmcnt(1)
	global_store_dwordx4 v[8:9], v[0:3], off
	s_nop 1
	v_add_u32_e32 v0, s60, v11
	v_mad_i64_i32 v[0:1], s[28:29], s24, v0, 0
	v_lshl_add_u64 v[0:1], v[0:1], 1, s[22:23]
	v_lshl_add_u64 v[0:1], v[0:1], 0, s[26:27]
	v_lshl_add_u64 v[0:1], v[0:1], 0, v[152:153]
	s_waitcnt lgkmcnt(0)
	global_store_dwordx4 v[0:1], v[4:7], off
	v_add_u32_e32 v0, 0x600, v10
	s_nop 0
	v_ashrrev_i32_e32 v4, 4, v0
	v_mad_u64_u32 v[0:1], s[28:29], v4, s51, v[152:153]
	v_add_u32_e32 v4, s60, v4
	v_mad_i64_i32 v[4:5], s[28:29], s24, v4, 0
	ds_read_b128 v[0:3], v0
	v_lshl_add_u64 v[4:5], v[4:5], 1, s[22:23]
	v_lshl_add_u64 v[4:5], v[4:5], 0, s[26:27]
	v_lshl_add_u64 v[8:9], v[4:5], 0, v[152:153]
	v_add_u32_e32 v4, 0x700, v10
	v_ashrrev_i32_e32 v11, 4, v4
	v_mad_u64_u32 v[4:5], s[28:29], v11, s51, v[152:153]
	ds_read_b128 v[4:7], v4
	s_waitcnt lgkmcnt(1)
	global_store_dwordx4 v[8:9], v[0:3], off
	s_nop 1
	v_add_u32_e32 v0, s60, v11
	v_mad_i64_i32 v[0:1], s[28:29], s24, v0, 0
	v_lshl_add_u64 v[0:1], v[0:1], 1, s[22:23]
	v_lshl_add_u64 v[0:1], v[0:1], 0, s[26:27]
	v_lshl_add_u64 v[0:1], v[0:1], 0, v[152:153]
	s_waitcnt lgkmcnt(0)
	global_store_dwordx4 v[0:1], v[4:7], off
	v_add_u32_e32 v0, 0x800, v10
	s_nop 0
	v_ashrrev_i32_e32 v4, 4, v0
	v_mad_u64_u32 v[0:1], s[28:29], v4, s51, v[152:153]
	v_add_u32_e32 v4, s60, v4
	v_mad_i64_i32 v[4:5], s[28:29], s24, v4, 0
	ds_read_b128 v[0:3], v0
	v_lshl_add_u64 v[4:5], v[4:5], 1, s[22:23]
	v_lshl_add_u64 v[4:5], v[4:5], 0, s[26:27]
	v_lshl_add_u64 v[8:9], v[4:5], 0, v[152:153]
	v_add_u32_e32 v4, 0x900, v10
	v_ashrrev_i32_e32 v11, 4, v4
	v_mad_u64_u32 v[4:5], s[28:29], v11, s51, v[152:153]
	ds_read_b128 v[4:7], v4
	s_waitcnt lgkmcnt(1)
	global_store_dwordx4 v[8:9], v[0:3], off
	s_nop 1
	v_add_u32_e32 v0, s60, v11
	v_mad_i64_i32 v[0:1], s[28:29], s24, v0, 0
	v_lshl_add_u64 v[0:1], v[0:1], 1, s[22:23]
	v_lshl_add_u64 v[0:1], v[0:1], 0, s[26:27]
	v_lshl_add_u64 v[0:1], v[0:1], 0, v[152:153]
	s_waitcnt lgkmcnt(0)
	global_store_dwordx4 v[0:1], v[4:7], off
	v_add_u32_e32 v0, 0xa00, v10
	s_nop 0
	v_ashrrev_i32_e32 v4, 4, v0
	v_mad_u64_u32 v[0:1], s[28:29], v4, s51, v[152:153]
	v_add_u32_e32 v4, s60, v4
	v_mad_i64_i32 v[4:5], s[28:29], s24, v4, 0
	ds_read_b128 v[0:3], v0
	v_lshl_add_u64 v[4:5], v[4:5], 1, s[22:23]
	v_lshl_add_u64 v[4:5], v[4:5], 0, s[26:27]
	v_lshl_add_u64 v[8:9], v[4:5], 0, v[152:153]
	v_add_u32_e32 v4, 0xb00, v10
	v_ashrrev_i32_e32 v11, 4, v4
	v_mad_u64_u32 v[4:5], s[28:29], v11, s51, v[152:153]
	ds_read_b128 v[4:7], v4
	s_waitcnt lgkmcnt(1)
	global_store_dwordx4 v[8:9], v[0:3], off
	s_nop 1
	v_add_u32_e32 v0, s60, v11
	v_mad_i64_i32 v[0:1], s[28:29], s24, v0, 0
	v_lshl_add_u64 v[0:1], v[0:1], 1, s[22:23]
	v_lshl_add_u64 v[0:1], v[0:1], 0, s[26:27]
	v_lshl_add_u64 v[0:1], v[0:1], 0, v[152:153]
	s_waitcnt lgkmcnt(0)
	global_store_dwordx4 v[0:1], v[4:7], off
	v_add_u32_e32 v0, 0xc00, v10
	s_nop 0
	v_ashrrev_i32_e32 v4, 4, v0
	v_mad_u64_u32 v[0:1], s[28:29], v4, s51, v[152:153]
	v_add_u32_e32 v4, s60, v4
	v_mad_i64_i32 v[4:5], s[28:29], s24, v4, 0
	ds_read_b128 v[0:3], v0
	v_lshl_add_u64 v[4:5], v[4:5], 1, s[22:23]
	v_lshl_add_u64 v[4:5], v[4:5], 0, s[26:27]
	v_lshl_add_u64 v[8:9], v[4:5], 0, v[152:153]
	v_add_u32_e32 v4, 0xd00, v10
	v_ashrrev_i32_e32 v11, 4, v4
	v_mad_u64_u32 v[4:5], s[28:29], v11, s51, v[152:153]
	ds_read_b128 v[4:7], v4
	s_waitcnt lgkmcnt(1)
	global_store_dwordx4 v[8:9], v[0:3], off
	s_nop 1
	v_add_u32_e32 v0, s60, v11
	v_mad_i64_i32 v[0:1], s[28:29], s24, v0, 0
	v_lshl_add_u64 v[0:1], v[0:1], 1, s[22:23]
	v_lshl_add_u64 v[0:1], v[0:1], 0, s[26:27]
	v_lshl_add_u64 v[0:1], v[0:1], 0, v[152:153]
	s_waitcnt lgkmcnt(0)
	global_store_dwordx4 v[0:1], v[4:7], off
	v_add_u32_e32 v0, 0xe00, v10
	s_nop 0
	v_ashrrev_i32_e32 v4, 4, v0
	v_mad_u64_u32 v[0:1], s[28:29], v4, s51, v[152:153]
	v_add_u32_e32 v4, s60, v4
	v_mad_i64_i32 v[4:5], s[28:29], s24, v4, 0
	ds_read_b128 v[0:3], v0
	v_lshl_add_u64 v[4:5], v[4:5], 1, s[22:23]
	v_lshl_add_u64 v[4:5], v[4:5], 0, s[26:27]
	v_lshl_add_u64 v[8:9], v[4:5], 0, v[152:153]
	v_add_u32_e32 v4, 0xf00, v10
	v_ashrrev_i32_e32 v10, 4, v4
	v_mad_u64_u32 v[4:5], s[28:29], v10, s51, v[152:153]
	ds_read_b128 v[4:7], v4
	s_waitcnt lgkmcnt(1)
	global_store_dwordx4 v[8:9], v[0:3], off
	s_nop 1
	v_add_u32_e32 v0, s60, v10
	v_mad_i64_i32 v[0:1], s[24:25], s24, v0, 0
	v_lshl_add_u64 v[0:1], v[0:1], 1, s[22:23]
	v_readlane_b32 s22, v245, 32
	v_lshl_add_u64 v[0:1], v[0:1], 0, s[26:27]
	s_add_i32 s59, s59, s22
	s_add_i32 s57, s57, s22
	v_lshl_add_u64 v[0:1], v[0:1], 0, v[152:153]
	s_cmp_gt_i32 s59, 63
	s_waitcnt lgkmcnt(0)
	global_store_dwordx4 v[0:1], v[4:7], off
	s_cbranch_scc1 .LBB0_264
